# one static s_setprio 1 for waves 0-3 before each GEMM phase K-loop (reset at phase end)
# speedup vs baseline: 1.0028x; 1.0028x over previous
.LBB0_378:
	s_lshl_b32 s65, s3, 6
	s_and_b32 s1, s1, 3
	v_or_b32_e32 v6, s65, v3
	v_lshlrev_b32_e32 v6, 7, v6
	s_lshl_b32 s3, s1, 5
	v_or_b32_e32 v8, v6, v192
	v_or_b32_e32 v9, v6, v193
	v_or_b32_e32 v6, s3, v3
	v_lshlrev_b32_e32 v6, 7, v6
	s_mov_b64 s[48:49], 0x80
	v_or_b32_e32 v10, v6, v192
	v_or_b32_e32 v11, v6, v193
	v_lshl_add_u64 v[6:7], v[4:5], 0, s[48:49]
	s_add_i32 m0, s79, 0x18000
	s_mov_b64 s[50:51], 0x40080
	s_waitcnt vmcnt(2)
	s_barrier
	global_load_lds_dwordx4 v[6:7], off
	v_lshl_add_u64 v[6:7], v[4:5], 0, s[50:51]
	s_add_i32 m0, s79, 0x1a000
	s_mov_b64 s[52:53], 0x10080
	global_load_lds_dwordx4 v[6:7], off
	v_lshl_add_u64 v[6:7], v[4:5], 0, s[52:53]
	s_add_i32 m0, s79, 0x1c000
	s_mov_b64 s[54:55], 0x50080
	global_load_lds_dwordx4 v[6:7], off
	v_lshl_add_u64 v[4:5], v[4:5], 0, s[54:55]
	s_add_i32 m0, s79, 0x1e000
	v_writelane_b32 v254, s34, 25
	global_load_lds_dwordx4 v[4:5], off
	s_nop 0
	v_writelane_b32 v254, s35, 26
	v_writelane_b32 v254, s26, 27
	s_cmpk_lt_u32 s0, 0x100
	v_or_b32_e32 v4, s3, v191
	v_writelane_b32 v254, s27, 28
	s_cselect_b64 s[56:57], -1, 0
	s_lshl_b32 s85, s1, 6
	s_ashr_i32 s3, s33, 31
	s_ashr_i32 s73, s2, 31
	v_readlane_b32 s0, v254, 13
	v_readlane_b32 s1, v254, 14
	s_add_u32 s58, s0, 0x783800
	s_addc_u32 s59, s1, 0
	s_add_u32 s60, s0, 0x784800
	s_mov_b32 s13, 0x14800
	s_addc_u32 s61, s1, 0
	s_addk_i32 s13, 0x100
	s_mov_b32 s12, 0x10800
	v_add_u32_e32 v205, s13, v10
	v_add_u32_e32 v206, s13, v11
	s_mov_b32 s13, 0x18800
	s_addk_i32 s12, 0x100
	s_addk_i32 s13, 0x100
	s_mov_b32 s8, 0x18000
	s_mov_b32 s9, 0x1c000
	s_waitcnt vmcnt(4)
	s_mov_b32 s1, 0x10000
	v_add_u32_e32 v201, s12, v10
	v_add_u32_e32 v202, s12, v11
	s_mov_b32 s12, 0x14000
	v_add_u32_e32 v209, s13, v10
	v_add_u32_e32 v210, s13, v11
	s_mov_b32 s13, 0x1c800
	v_lshlrev_b32_e32 v160, 1, v191
	s_addk_i32 s1, 0x100
	s_addk_i32 s12, 0x100
	s_addk_i32 s13, 0x100
	s_movk_i32 s68, 0xfc40
	s_movk_i32 s92, 0xa040
	s_add_i32 s70, s8, 0x100
	s_add_i32 s71, s9, 0x100
	v_or_b32_e32 v198, 0xfffff900, v4
	v_cmp_gt_u32_e64 s[6:7], 8, v3
	v_lshl_add_u64 v[162:163], s[42:43], 0, v[160:161]
	v_lshl_add_u64 v[164:165], s[34:35], 0, v[160:161]
	v_lshl_add_u64 v[166:167], s[26:27], 0, v[160:161]
	v_add_u32_e32 v168, v194, v186
	v_mov_b32_e32 v169, v161
	s_mov_b32 s0, 0
	v_mov_b64_e32 v[170:171], 0x580
	v_mov_b64_e32 v[172:173], 0x57f
	v_add_u32_e32 v199, s1, v10
	v_add_u32_e32 v200, s1, v11
	v_add_u32_e32 v203, s12, v10
	v_add_u32_e32 v204, s12, v11
	v_add_u32_e32 v207, 0x100, v8
	v_add_u32_e32 v208, 0x100, v9
	v_add_u32_e32 v211, s13, v10
	v_add_u32_e32 v212, s13, v11
	s_movk_i32 s13, 0xc00
	s_mov_b32 s69, -1
	s_mov_b32 s72, 0x3e000000
	s_mov_b32 s93, -1
	v_add_u32_e32 v213, s70, v10
	v_add_u32_e32 v214, s70, v11
	v_add_u32_e32 v215, s71, v10
	v_add_u32_e32 v216, s71, v11
	v_readfirstlane_b32 s101, v156
	s_nop 0
	s_cmpk_lt_u32 s101, 0x100
	s_cbranch_scc0 .Lprio_skip_p1
	s_setprio 1

.LBB0_765:
	s_mov_b64 s[24:25], 0x80
	v_lshl_add_u64 v[10:11], v[6:7], 0, s[24:25]
	s_add_i32 m0, s66, 0x18000
	s_mov_b64 s[50:51], 0x60080
	s_waitcnt vmcnt(2)
	s_barrier
	global_load_lds_dwordx4 v[10:11], off
	v_lshl_add_u64 v[10:11], v[6:7], 0, s[50:51]
	s_add_i32 m0, s66, 0x1a000
	s_mov_b64 s[52:53], 0x18080
	global_load_lds_dwordx4 v[10:11], off
	v_lshl_add_u64 v[10:11], v[6:7], 0, s[52:53]
	s_add_i32 m0, s66, 0x1c000
	s_mov_b64 s[54:55], 0x78080
	global_load_lds_dwordx4 v[10:11], off
	v_lshl_add_u64 v[6:7], v[6:7], 0, s[54:55]
	s_add_i32 m0, s66, 0x1e000
	s_and_b32 s0, s0, 3
	global_load_lds_dwordx4 v[6:7], off
	v_lshl_or_b32 v9, s0, 12, v172
	v_or_b32_e32 v159, v9, v192
	v_or_b32_e32 v173, v9, v193
	v_cmp_gt_u32_e64 s[8:9], 8, v3
	v_mov_b32_e32 v9, 0xffffc040
	v_lshl_or_b32 v1, s1, 6, v3
	v_cndmask_b32_e64 v148, v9, 0, s[8:9]
	v_mov_b32_e32 v9, 0x4040
	s_lshl_b32 s0, s0, 6
	v_cndmask_b32_e64 v150, 0, v9, s[8:9]
	v_lshlrev_b32_e32 v9, 10, v1
	s_cmpk_lt_u32 s10, 0x100
	v_or_b32_e32 v174, s0, v191
	v_or3_b32 v175, v191, v9, s0
	s_mov_b32 s0, 0x10000
	s_cselect_b64 s[56:57], -1, 0
	s_add_i32 s73, s0, 0x100
	s_mov_b32 s0, 0x10800
	s_add_i32 s77, s0, 0x100
	s_mov_b32 s0, 0x14000
	s_add_i32 s79, s0, 0x100
	s_mov_b32 s0, 0x14800
	v_lshlrev_b32_e32 v6, 7, v1
	s_waitcnt vmcnt(4)
	s_add_i32 s80, s0, 0x100
	s_mov_b32 s0, 0x18800
	v_or_b32_e32 v7, v6, v192
	v_or_b32_e32 v6, v6, v193
	s_mov_b32 s1, 0x18000
	s_mov_b32 s11, 0x1c000
	v_and_b32_e32 v4, 7, v4
	v_lshlrev_b32_e32 v8, 1, v8
	s_add_i32 s81, s0, 0x100
	s_mov_b32 s0, 0x1c800
	s_movk_i32 s58, 0xc040
	s_mov_b32 s70, 0
	v_cndmask_b32_e64 v149, -1, 0, s[8:9]
	v_mov_b32_e32 v151, v5
	s_ashr_i32 s71, s33, 31
	s_ashr_i32 s72, s2, 31
	v_lshl_add_u32 v152, v4, 4, v8
	v_mov_b32_e32 v153, v5
	v_mov_b64_e32 v[154:155], 0x100
	v_mov_b64_e32 v[160:161], 0xff
	v_add_u32_e32 v176, 0x100, v7
	v_add_u32_e32 v177, 0x100, v6
	s_add_i32 s82, s0, 0x100
	s_mov_b32 s59, -1
	s_mov_b64 s[60:61], 0x4040
	s_add_i32 s83, s1, 0x100
	s_add_i32 s84, s11, 0x100
	v_mov_b64_e32 v[162:163], 0x40000
	v_mov_b64_e32 v[164:165], 0x48000
	v_mov_b64_e32 v[166:167], 0x50000
	v_mov_b64_e32 v[168:169], 0x58000
	v_readfirstlane_b32 s101, v156
	s_nop 0
	s_cmpk_lt_u32 s101, 0x100
	s_cbranch_scc0 .Lprio_skip_p3
	s_setprio 1

.LBB0_964:
	s_mov_b64 s[36:37], 0x80
	v_lshl_add_u64 v[134:135], v[132:133], 0, s[36:37]
	s_add_i32 m0, s5, 0x18000
	s_mov_b64 s[44:45], 0x40080
	s_waitcnt vmcnt(2)
	s_barrier
	global_load_lds_dwordx4 v[134:135], off
	v_lshl_add_u64 v[134:135], v[132:133], 0, s[44:45]
	s_add_i32 m0, s5, 0x1a000
	s_mov_b64 s[46:47], 0x10080
	global_load_lds_dwordx4 v[134:135], off
	v_lshl_add_u64 v[134:135], v[132:133], 0, s[46:47]
	s_add_i32 m0, s5, 0x1c000
	s_mov_b64 s[50:51], 0x50080
	global_load_lds_dwordx4 v[134:135], off
	v_lshl_add_u64 v[132:133], v[132:133], 0, s[50:51]
	s_add_i32 m0, s5, 0x1e000
	s_cmpk_lt_u32 s39, 0x100
	global_load_lds_dwordx4 v[132:133], off
	v_or_b32_e32 v165, s12, v191
	s_mov_b32 s12, 0x10000
	v_or_b32_e32 v162, s52, v3
	s_cselect_b64 s[52:53], -1, 0
	s_add_i32 s72, s12, 0x100
	s_mov_b32 s12, 0x10800
	v_lshlrev_b32_e32 v132, 7, v162
	s_add_i32 s73, s12, 0x100
	s_mov_b32 s12, 0x14800
	v_or_b32_e32 v133, v132, v192
	v_or_b32_e32 v134, v132, v193
	v_lshl_or_b32 v132, s3, 12, v172
	s_waitcnt vmcnt(4)
	s_add_i32 s79, s12, 0x100
	s_mov_b32 s12, 0x18800
	v_or_b32_e32 v163, v132, v192
	v_or_b32_e32 v164, v132, v193
	s_mov_b32 s14, 0x18000
	s_mov_b32 s15, 0x1c000
	v_mov_b32_e32 v132, 0
	v_add_u32_e32 v166, 0x100, v133
	s_add_i32 s80, s12, 0x100
	s_mov_b32 s12, 0x1c800
	s_movk_i32 s56, 0xc040
	v_mbcnt_lo_u32_b32 v133, -1, 0
	v_cmp_gt_u32_e64 s[8:9], 8, v3
	s_mov_b32 s55, 0
	v_cmp_eq_u32_e64 s[10:11], 0, v190
	s_ashr_i32 s39, s2, 31
	v_add_u32_e32 v142, v194, v186
	v_mov_b32_e32 v143, v132
	s_add_i32 s77, s13, 0x100
	v_add_u32_e32 v167, 0x100, v134
	s_add_i32 s81, s12, 0x100
	s_mov_b32 s57, -1
	s_mov_b64 s[58:59], 0x4040
	v_mbcnt_hi_u32_b32 v168, -1, v133
	v_mov_b64_e32 v[144:145], 0x100
	v_mov_b64_e32 v[146:147], 0xff
	s_add_i32 s82, s14, 0x100
	s_add_i32 s83, s15, 0x100
	s_mov_b32 s84, 0
	v_readfirstlane_b32 s101, v156
	s_nop 0
	s_cmpk_lt_u32 s101, 0x100
	s_cbranch_scc0 .Lprio_skip_p4
	s_setprio 1

.LBB0_1125:
	s_mov_b64 s[22:23], 0x80
	v_lshl_add_u64 v[6:7], v[4:5], 0, s[22:23]
	s_add_i32 m0, s34, 0x18000
	s_mov_b64 s[24:25], 0x40080
	s_waitcnt vmcnt(2)
	s_barrier
	global_load_lds_dwordx4 v[6:7], off
	v_lshl_add_u64 v[6:7], v[4:5], 0, s[24:25]
	s_add_i32 m0, s34, 0x1a000
	s_mov_b64 s[28:29], 0x10080
	global_load_lds_dwordx4 v[6:7], off
	v_lshl_add_u64 v[6:7], v[4:5], 0, s[28:29]
	s_add_i32 m0, s34, 0x1c000
	s_mov_b64 s[36:37], 0x50080
	global_load_lds_dwordx4 v[6:7], off
	v_lshl_add_u64 v[4:5], v[4:5], 0, s[36:37]
	s_add_i32 m0, s34, 0x1e000
	s_and_b32 s45, s4, 3
	global_load_lds_dwordx4 v[4:5], off
	s_cmpk_lt_u32 s10, 0x100
	s_cselect_b64 s[40:41], -1, 0
	s_lshl_b32 s10, s11, 8
	s_addk_i32 s10, 0x100
	s_add_i32 s10, s10, 0x27400
	v_lshl_or_b32 v6, s45, 12, v172
	v_lshl_add_u32 v143, v3, 2, s10
	s_mov_b32 s10, 0x10800
	v_or_b32_e32 v7, v6, v192
	v_or_b32_e32 v6, v6, v193
	s_addk_i32 s10, 0x100
	v_add_u32_e32 v147, s10, v7
	v_add_u32_e32 v148, s10, v6
	s_mov_b32 s10, 0x14800
	s_addk_i32 s10, 0x100
	v_add_u32_e32 v151, s10, v7
	v_add_u32_e32 v152, s10, v6
	s_mov_b32 s10, 0x18800
	v_lshl_or_b32 v142, s11, 6, v3
	s_addk_i32 s10, 0x100
	v_lshlrev_b32_e32 v4, 7, v142
	s_mov_b32 s56, 0x18000
	s_mov_b32 s57, 0x1c000
	s_waitcnt vmcnt(4)
	v_add_u32_e32 v155, s10, v7
	v_add_u32_e32 v160, s10, v6
	s_mov_b32 s10, 0x1c800
	v_or_b32_e32 v5, v4, v192
	v_or_b32_e32 v4, v4, v193
	v_lshl_or_b32 v144, s45, 6, v191
	s_mov_b32 s45, 0
	s_add_i32 s67, s46, 0x100
	s_add_i32 s72, s44, 0x100
	s_addk_i32 s10, 0x100
	s_mov_b32 s46, 0xffff0040
	s_add_i32 s73, s56, 0x100
	s_add_i32 s77, s57, 0x100
	v_cmp_gt_u32_e64 s[4:5], 8, v3
	s_ashr_i32 s65, s2, 31
	v_add_u32_e32 v132, v194, v186
	v_mov_b32_e32 v133, v159
	v_mov_b64_e32 v[134:135], 0x400
	v_mov_b64_e32 v[136:137], 0x3ff
	v_add_u32_e32 v145, s67, v7
	v_add_u32_e32 v146, s67, v6
	v_add_u32_e32 v149, s72, v7
	v_add_u32_e32 v150, s72, v6
	v_add_u32_e32 v153, 0x100, v5
	v_add_u32_e32 v154, 0x100, v4
	v_add_u32_e32 v161, s10, v7
	v_add_u32_e32 v162, s10, v6
	s_mov_b32 s47, -1
	s_mov_b64 s[48:49], 0x10040
	s_mov_b64 s[50:51], 0x130040
	s_mov_b64 s[52:53], 0x160000
	s_mov_b64 s[54:55], 0x150040
	v_add_u32_e32 v163, s73, v7
	v_add_u32_e32 v164, s73, v6
	v_add_u32_e32 v165, s77, v7
	v_add_u32_e32 v166, s77, v6
	s_mov_b32 s44, s45
	v_readfirstlane_b32 s101, v156
	s_nop 0
	s_cmpk_lt_u32 s101, 0x100
	s_cbranch_scc0 .Lprio_skip_p5
	s_setprio 1

.LBB0_1361:
	s_mov_b64 s[24:25], 0x80
	v_lshl_add_u64 v[8:9], v[4:5], 0, s[24:25]
	s_add_i32 m0, s35, 0x18000
	s_mov_b64 s[28:29], 0x100080
	s_waitcnt vmcnt(2)
	s_barrier
	global_load_lds_dwordx4 v[8:9], off
	v_lshl_add_u64 v[8:9], v[4:5], 0, s[28:29]
	s_add_i32 m0, s35, 0x1a000
	s_mov_b64 s[36:37], 0x40080
	global_load_lds_dwordx4 v[8:9], off
	v_lshl_add_u64 v[8:9], v[4:5], 0, s[36:37]
	s_add_i32 m0, s35, 0x1c000
	s_mov_b64 s[40:41], 0x140080
	global_load_lds_dwordx4 v[8:9], off
	v_lshl_add_u64 v[4:5], v[4:5], 0, s[40:41]
	s_add_i32 m0, s35, 0x1e000
	v_lshrrev_b32_e32 v142, 4, v157
	global_load_lds_dwordx4 v[4:5], off
	s_lshl_b32 s62, s4, 6
	v_or_b32_e32 v168, s62, v3
	v_xor_b32_e32 v5, v142, v187
	v_bitop3_b32 v7, v142, v187, 4 bitop3:0x36
	s_and_b32 s9, s1, 3
	v_lshlrev_b32_e32 v4, 7, v168
	v_lshlrev_b32_e32 v5, 4, v5
	v_lshlrev_b32_e32 v7, 4, v7
	v_or_b32_e32 v8, v4, v5
	v_or_b32_e32 v9, v4, v7
	v_lshl_or_b32 v4, s9, 12, v172
	s_add_i32 s66, s5, 0x100
	s_mov_b32 s5, 0x14800
	v_or_b32_e32 v144, v4, v7
	s_waitcnt vmcnt(4)
	v_add_u32_e32 v134, v6, v186
	v_mov_b32_e32 v6, v133
	v_mov_b32_e32 v7, v133
	s_add_i32 s67, s5, 0x100
	s_mov_b32 s5, 0x18800
	v_or_b32_e32 v143, v4, v5
	s_mov_b32 s4, 0x18000
	s_mov_b32 s7, 0x1c000
	v_mov_b32_e32 v4, v133
	v_mov_b32_e32 v5, v133
	s_add_i32 s64, s6, 0x100
	s_mov_b32 s6, 0x10800
	v_add_u32_e32 v145, 0x100, v8
	v_add_u32_e32 v146, 0x100, v9
	s_add_i32 s68, s5, 0x100
	s_mov_b32 s5, 0x1c800
	v_mov_b64_e32 v[10:11], v[6:7]
	v_mov_b64_e32 v[22:23], v[6:7]
	v_mov_b64_e32 v[26:27], v[6:7]
	v_mov_b64_e32 v[38:39], v[6:7]
	v_mov_b64_e32 v[42:43], v[6:7]
	v_mov_b64_e32 v[54:55], v[6:7]
	v_mov_b64_e32 v[58:59], v[6:7]
	v_mov_b64_e32 v[14:15], v[6:7]
	v_mov_b64_e32 v[18:19], v[6:7]
	v_mov_b64_e32 v[30:31], v[6:7]
	v_mov_b64_e32 v[34:35], v[6:7]
	v_mov_b64_e32 v[46:47], v[6:7]
	v_mov_b64_e32 v[50:51], v[6:7]
	v_mov_b64_e32 v[62:63], v[6:7]
	v_mov_b64_e32 v[66:67], v[6:7]
	v_mov_b64_e32 v[70:71], v[6:7]
	v_mov_b64_e32 v[74:75], v[6:7]
	v_mov_b64_e32 v[86:87], v[6:7]
	v_mov_b64_e32 v[90:91], v[6:7]
	v_mov_b64_e32 v[102:103], v[6:7]
	v_mov_b64_e32 v[106:107], v[6:7]
	v_mov_b64_e32 v[118:119], v[6:7]
	v_mov_b64_e32 v[122:123], v[6:7]
	v_mov_b64_e32 v[78:79], v[6:7]
	v_mov_b64_e32 v[82:83], v[6:7]
	v_mov_b64_e32 v[94:95], v[6:7]
	v_mov_b64_e32 v[98:99], v[6:7]
	v_mov_b64_e32 v[110:111], v[6:7]
	v_mov_b64_e32 v[114:115], v[6:7]
	v_mov_b64_e32 v[126:127], v[6:7]
	v_mov_b64_e32 v[130:131], v[6:7]
	s_sext_i32_i8 s0, s0
	v_mov_b32_e32 v135, v133
	s_mov_b32 s63, 0
	v_mov_b64_e32 v[136:137], 0x100
	v_mov_b64_e32 v[138:139], 0xff
	s_add_i32 s65, s6, 0x100
	s_mov_b64 s[44:45], 0x80080
	s_mov_b64 s[46:47], 0x180080
	s_add_i32 s69, s5, 0x100
	s_add_i32 s70, s4, 0x100
	s_add_i32 s71, s7, 0x100
	v_mov_b64_e32 v[8:9], v[4:5]
	v_mov_b64_e32 v[20:21], v[4:5]
	v_mov_b64_e32 v[24:25], v[4:5]
	v_mov_b64_e32 v[36:37], v[4:5]
	v_mov_b64_e32 v[40:41], v[4:5]
	v_mov_b64_e32 v[52:53], v[4:5]
	v_mov_b64_e32 v[56:57], v[4:5]
	v_mov_b64_e32 v[12:13], v[4:5]
	v_mov_b64_e32 v[16:17], v[4:5]
	v_mov_b64_e32 v[28:29], v[4:5]
	v_mov_b64_e32 v[32:33], v[4:5]
	v_mov_b64_e32 v[44:45], v[4:5]
	v_mov_b64_e32 v[48:49], v[4:5]
	v_mov_b64_e32 v[60:61], v[4:5]
	v_mov_b64_e32 v[64:65], v[4:5]
	v_mov_b64_e32 v[68:69], v[4:5]
	v_mov_b64_e32 v[72:73], v[4:5]
	v_mov_b64_e32 v[84:85], v[4:5]
	v_mov_b64_e32 v[88:89], v[4:5]
	v_mov_b64_e32 v[100:101], v[4:5]
	v_mov_b64_e32 v[104:105], v[4:5]
	v_mov_b64_e32 v[116:117], v[4:5]
	v_mov_b64_e32 v[120:121], v[4:5]
	v_mov_b64_e32 v[76:77], v[4:5]
	v_mov_b64_e32 v[80:81], v[4:5]
	v_mov_b64_e32 v[92:93], v[4:5]
	v_mov_b64_e32 v[96:97], v[4:5]
	v_mov_b64_e32 v[108:109], v[4:5]
	v_mov_b64_e32 v[112:113], v[4:5]
	v_mov_b64_e32 v[124:125], v[4:5]
	v_mov_b64_e32 v[128:129], v[4:5]
	v_readfirstlane_b32 s101, v156
	s_nop 0
	s_cmpk_lt_u32 s101, 0x100
	s_cbranch_scc0 .Lprio_skip_p6
	s_setprio 1
